# attention: causal/window masks computed arithmetically per lane (add+compare) instead of reading 40 spilled 64-bit lane masks back with v_readlane
# speedup vs baseline: 1.0150x; 1.0033x over previous
.LBB0_752:
	s_or_b64 exec, exec, s[70:71]
	s_ashr_i32 s70, s78, 11
	s_lshl_b32 vcc_lo, s70, 1
	s_and_b32 s69, s78, 0x7f
	s_bfm_b32 s71, vcc_lo, 0
	s_and_b32 s71, s71, s69
	s_bfe_u32 s79, s78, 0x40007
	s_lshr_b32 s72, s69, vcc_lo
	v_add_u32_e32 v2, s68, v138
	s_add_u32 s64, s50, s64
	v_ashrrev_i32_e32 v3, 31, v2
	s_addc_u32 s65, s51, s65
	v_lshlrev_b64 v[2:3], 7, v[2:3]
	v_lshl_add_u64 v[2:3], s[64:65], 0, v[2:3]
	v_mov_b32_e32 v131, v1
	v_lshl_add_u64 v[2:3], v[2:3], 0, v[130:131]
	global_load_dwordx4 v[80:83], v[2:3], off
	global_load_dwordx4 v[84:87], v[2:3], off offset:64
	ds_read_b128 v[96:99], v141 offset:36864
	ds_read_b128 v[100:103], v141 offset:36928
	s_waitcnt vmcnt(13) lgkmcnt(1)
	v_mfma_f32_16x16x32_bf16 v[96:99], v[96:99], v[88:91], 0
	v_lshl_add_u32 v0, s72, 7, v138
	s_cmp_lg_u32 s72, 0
	s_cselect_b32 s100, 0, 0x80
	v_lshrrev_b32_e32 v178, 6, v202
	v_and_b32_e32 v179, 15, v202
	v_lshl_or_b32 v178, v178, 4, v179
	v_lshrrev_b32_e32 v179, 7, v202
	v_bfe_u32 v180, v202, 4, 2
	v_lshlrev_b32_e32 v180, 2, v180
	v_lshl_add_u32 v179, v179, 5, v180
	v_max_u32_e32 v180, s100, v178
	v_sub_u32_e32 v175, v179, v180
	v_sub_u32_e32 v176, v178, v180
	v_add_u32_e32 v176, 0x81, v176
	s_waitcnt vmcnt(12) lgkmcnt(0)
	v_mfma_f32_16x16x32_bf16 v[152:155], v[100:103], v[92:95], v[96:99]
	ds_read_b128 v[100:103], v142 offset:36928
	v_lshlrev_b32_e32 v0, vcc_lo, v0
	ds_read_b128 v[96:99], v142 offset:36864
	s_waitcnt lgkmcnt(0)
	v_mfma_f32_16x16x32_bf16 v[96:99], v[96:99], v[88:91], 0
	v_mfma_f32_16x16x32_bf16 v[124:127], v[100:103], v[92:95], v[96:99]
	ds_read_b128 v[100:103], v143 offset:36928
	s_nop 0
	ds_read_b128 v[96:99], v143 offset:36864
	s_waitcnt lgkmcnt(0)
	v_mfma_f32_16x16x32_bf16 v[96:99], v[96:99], v[88:91], 0
	v_add_u32_e32 v177, 0, v175
	v_cmp_lt_u32_e32 vcc, v177, v176
	s_nop 1
	v_cndmask_b32_e32 v3, v213, v152, vcc
	v_mfma_f32_16x16x32_bf16 v[120:123], v[100:103], v[92:95], v[96:99]
	ds_read_b128 v[100:103], v144 offset:36928
	s_nop 0
	ds_read_b128 v[96:99], v144 offset:36864
	s_waitcnt lgkmcnt(0)
	v_mfma_f32_16x16x32_bf16 v[96:99], v[96:99], v[88:91], 0
	s_mov_b32 s68, 0xff61b1e6
	v_mfma_f32_16x16x32_bf16 v[116:119], v[100:103], v[92:95], v[96:99]
	ds_read_b128 v[100:103], v145 offset:36928
	v_add_u32_e32 v177, 1, v175
	v_cmp_lt_u32_e32 vcc, v177, v176
	s_nop 1
	v_cndmask_b32_e32 v2, v213, v153, vcc
	s_nop 0
	ds_read_b128 v[96:99], v145 offset:36864
	s_waitcnt lgkmcnt(0)
	v_mfma_f32_16x16x32_bf16 v[96:99], v[96:99], v[88:91], 0
	ds_read_b128 v[160:163], v149 offset:36928
	v_mfma_f32_16x16x32_bf16 v[112:115], v[100:103], v[92:95], v[96:99]
	ds_read_b128 v[100:103], v146 offset:36928
	s_nop 3
	ds_read_b128 v[96:99], v146 offset:36864
	s_waitcnt lgkmcnt(0)
	v_mfma_f32_16x16x32_bf16 v[96:99], v[96:99], v[88:91], 0
	v_mfma_f32_16x16x32_bf16 v[108:111], v[100:103], v[92:95], v[96:99]
	ds_read_b128 v[100:103], v147 offset:36928
	s_nop 5
	ds_read_b128 v[96:99], v147 offset:36864
	s_waitcnt lgkmcnt(0)
	v_mfma_f32_16x16x32_bf16 v[96:99], v[96:99], v[88:91], 0
	v_mfma_f32_16x16x32_bf16 v[104:107], v[100:103], v[92:95], v[96:99]
	ds_read_b128 v[100:103], v148 offset:36928
	s_nop 5
	ds_read_b128 v[96:99], v148 offset:36864
	s_waitcnt lgkmcnt(0)
	v_mfma_f32_16x16x32_bf16 v[96:99], v[96:99], v[88:91], 0
	v_mfma_f32_16x16x32_bf16 v[100:103], v[100:103], v[92:95], v[96:99]
	s_nop 6
	ds_read_b128 v[96:99], v149 offset:36864
	s_waitcnt lgkmcnt(0)
	v_mfma_f32_16x16x32_bf16 v[96:99], v[96:99], v[88:91], 0
	v_mfma_f32_16x16x32_bf16 v[96:99], v[160:163], v[92:95], v[96:99]
	ds_read_b128 v[160:163], v150 offset:36864
	s_waitcnt lgkmcnt(0)
	v_mfma_f32_16x16x32_bf16 v[88:91], v[160:163], v[88:91], 0
	ds_read_b128 v[160:163], v150 offset:36928
	s_waitcnt lgkmcnt(0)
	v_mfma_f32_16x16x32_bf16 v[88:91], v[160:163], v[92:95], v[88:91]
	v_max3_f32 v94, v3, s68, v2
	v_add_u32_e32 v177, 2, v175
	v_cmp_lt_u32_e32 vcc, v177, v176
	s_nop 1
	v_cndmask_b32_e32 v92, v213, v154, vcc
	v_add_u32_e32 v177, 3, v175
	v_cmp_lt_u32_e32 vcc, v177, v176
	s_nop 1
	v_cndmask_b32_e32 v93, v213, v155, vcc
	v_add_u32_e32 v177, 16, v175
	v_cmp_lt_u32_e32 vcc, v177, v176
	s_nop 1
	v_cndmask_b32_e32 v95, v213, v124, vcc
	v_max3_f32 v129, v94, v92, v93
	v_add_u32_e32 v177, 17, v175
	v_cmp_lt_u32_e32 vcc, v177, v176
	s_nop 1
	v_cndmask_b32_e32 v94, v213, v125, vcc
	v_add_u32_e32 v177, 18, v175
	v_cmp_lt_u32_e32 vcc, v177, v176
	s_nop 1
	v_cndmask_b32_e32 v124, v213, v126, vcc
	v_add_u32_e32 v177, 19, v175
	v_cmp_lt_u32_e32 vcc, v177, v176
	s_nop 1
	v_cndmask_b32_e32 v125, v213, v127, vcc
	v_add_u32_e32 v177, 32, v175
	v_cmp_lt_u32_e32 vcc, v177, v176
	s_nop 1
	v_cndmask_b32_e32 v126, v213, v120, vcc
	v_add_u32_e32 v177, 33, v175
	v_cmp_lt_u32_e32 vcc, v177, v176
	s_nop 1
	v_cndmask_b32_e32 v120, v213, v121, vcc
	v_add_u32_e32 v177, 34, v175
	v_cmp_lt_u32_e32 vcc, v177, v176
	s_nop 1
	v_cndmask_b32_e32 v121, v213, v122, vcc
	v_add_u32_e32 v177, 35, v175
	v_cmp_lt_u32_e32 vcc, v177, v176
	s_nop 1
	v_cndmask_b32_e32 v122, v213, v123, vcc
	v_add_u32_e32 v177, 48, v175
	v_cmp_lt_u32_e32 vcc, v177, v176
	s_nop 1
	v_cndmask_b32_e32 v123, v213, v116, vcc
	v_add_u32_e32 v177, 49, v175
	v_cmp_lt_u32_e32 vcc, v177, v176
	s_nop 1
	v_cndmask_b32_e32 v116, v213, v117, vcc
	v_add_u32_e32 v177, 50, v175
	v_cmp_lt_u32_e32 vcc, v177, v176
	s_nop 1
	v_cndmask_b32_e32 v117, v213, v118, vcc
	v_add_u32_e32 v177, 51, v175
	v_cmp_lt_u32_e32 vcc, v177, v176
	s_nop 1
	v_cndmask_b32_e32 v118, v213, v119, vcc
	v_add_u32_e32 v177, 64, v175
	v_cmp_lt_u32_e32 vcc, v177, v176
	s_nop 1
	v_cndmask_b32_e32 v119, v213, v112, vcc
	v_add_u32_e32 v177, 0x41, v175
	v_cmp_lt_u32_e32 vcc, v177, v176
	s_nop 1
	v_cndmask_b32_e32 v112, v213, v113, vcc
	v_add_u32_e32 v177, 0x42, v175
	v_cmp_lt_u32_e32 vcc, v177, v176
	s_nop 1
	v_cndmask_b32_e32 v113, v213, v114, vcc
	v_add_u32_e32 v177, 0x43, v175
	v_cmp_lt_u32_e32 vcc, v177, v176
	s_nop 1
	v_cndmask_b32_e32 v114, v213, v115, vcc
	v_add_u32_e32 v177, 0x50, v175
	v_cmp_lt_u32_e32 vcc, v177, v176
	s_nop 1
	v_cndmask_b32_e32 v115, v213, v108, vcc
	v_add_u32_e32 v177, 0x51, v175
	v_cmp_lt_u32_e32 vcc, v177, v176
	s_nop 1
	v_cndmask_b32_e32 v108, v213, v109, vcc
	v_add_u32_e32 v177, 0x52, v175
	v_cmp_lt_u32_e32 vcc, v177, v176
	s_nop 1
	v_cndmask_b32_e32 v109, v213, v110, vcc
	v_add_u32_e32 v177, 0x53, v175
	v_cmp_lt_u32_e32 vcc, v177, v176
	s_nop 1
	v_cndmask_b32_e32 v110, v213, v111, vcc
	v_max3_f32 v129, v129, v95, v94
	v_add_u32_e32 v177, 0x60, v175
	v_cmp_lt_u32_e32 vcc, v177, v176
	s_nop 1
	v_cndmask_b32_e32 v111, v213, v104, vcc
	v_max3_f32 v127, v129, v124, v125
	v_max3_f32 v127, v127, v126, v120
	v_add_u32_e32 v177, 0x61, v175
	v_cmp_lt_u32_e32 vcc, v177, v176
	s_nop 1
	v_cndmask_b32_e32 v104, v213, v105, vcc
	v_max3_f32 v127, v127, v121, v122
	v_max3_f32 v127, v127, v123, v116
	v_max3_f32 v127, v127, v117, v118
	v_add_u32_e32 v177, 0x62, v175
	v_cmp_lt_u32_e32 vcc, v177, v176
	s_nop 1
	v_cndmask_b32_e32 v105, v213, v106, vcc
	v_max3_f32 v127, v127, v119, v112
	v_max3_f32 v127, v127, v113, v114
	v_max3_f32 v127, v127, v115, v108
	v_add_u32_e32 v177, 0x63, v175
	v_cmp_lt_u32_e32 vcc, v177, v176
	s_nop 1
	v_cndmask_b32_e32 v107, v213, v107, vcc
	v_max3_f32 v127, v127, v109, v110
	v_max3_f32 v127, v127, v111, v104
	v_max3_f32 v106, v127, v105, v107
	v_add_u32_e32 v177, 0x70, v175
	v_cmp_lt_u32_e32 vcc, v177, v176
	s_nop 1
	v_cndmask_b32_e32 v127, v213, v100, vcc
	v_add_u32_e32 v177, 0x71, v175
	v_cmp_lt_u32_e32 vcc, v177, v176
	s_nop 1
	v_cndmask_b32_e32 v100, v213, v101, vcc
	v_add_u32_e32 v177, 0x72, v175
	v_cmp_lt_u32_e32 vcc, v177, v176
	s_nop 1
	v_cndmask_b32_e32 v101, v213, v102, vcc
	v_add_u32_e32 v177, 0x73, v175
	v_cmp_lt_u32_e32 vcc, v177, v176
	s_nop 1
	v_cndmask_b32_e32 v102, v213, v103, vcc
	v_add_u32_e32 v177, 0x80, v175
	v_cmp_lt_u32_e32 vcc, v177, v176
	s_nop 1
	v_cndmask_b32_e32 v103, v213, v96, vcc
	v_add_u32_e32 v177, 0x81, v175
	v_cmp_lt_u32_e32 vcc, v177, v176
	s_nop 1
	v_cndmask_b32_e32 v96, v213, v97, vcc
	v_add_u32_e32 v177, 0x82, v175
	v_cmp_lt_u32_e32 vcc, v177, v176
	s_nop 1
	v_cndmask_b32_e32 v97, v213, v98, vcc
	v_add_u32_e32 v177, 0x83, v175
	v_cmp_lt_u32_e32 vcc, v177, v176
	s_nop 1
	v_cndmask_b32_e32 v99, v213, v99, vcc
	v_add_u32_e32 v177, 0x90, v175
	v_cmp_lt_u32_e32 vcc, v177, v176
	s_nop 1
	v_cndmask_b32_e32 v129, v213, v88, vcc
	v_max3_f32 v106, v106, v127, v100
	v_add_u32_e32 v177, 0x91, v175
	v_cmp_lt_u32_e32 vcc, v177, v176
	s_nop 1
	v_cndmask_b32_e32 v98, v213, v89, vcc
	v_max3_f32 v106, v106, v101, v102
	v_max3_f32 v106, v106, v103, v96
	v_max3_f32 v106, v106, v97, v99
	v_add_u32_e32 v177, 0x92, v175
	v_cmp_lt_u32_e32 vcc, v177, v176
	s_nop 1
	v_cndmask_b32_e32 v90, v213, v90, vcc
	v_max3_f32 v88, v106, v129, v98
	v_add_u32_e32 v177, 0x93, v175
	v_cmp_lt_u32_e32 vcc, v177, v176
	s_nop 1
	v_cndmask_b32_e32 v89, v213, v91, vcc
	v_cmp_lt_i32_e32 vcc, v209, v210
	v_max3_f32 v91, v88, v90, v89
	s_nop 0
	v_cndmask_b32_e32 v88, v208, v209, vcc
	v_lshlrev_b32_e32 v88, 2, v88
	ds_bpermute_b32 v106, v88, v91
	v_cmp_lt_i32_e32 vcc, v211, v210
	s_waitcnt lgkmcnt(0)
	v_max_f32_e32 v106, v106, v106
	v_max_f32_e32 v91, v91, v106
	v_cndmask_b32_e32 v106, v208, v211, vcc
	v_lshlrev_b32_e32 v131, 2, v106
	ds_bpermute_b32 v106, v131, v91
	s_waitcnt lgkmcnt(0)
	v_max_f32_e32 v106, v106, v106
	v_max_f32_e32 v106, v91, v106
	v_sub_f32_e32 v3, v3, v106
	v_mul_f32_e32 v3, 0x3fb8aa3b, v3
	v_sub_f32_e32 v2, v2, v106
	v_exp_f32_e32 v3, v3
	v_mul_f32_e32 v2, 0x3fb8aa3b, v2
	v_exp_f32_e32 v135, v2
	v_sub_f32_e32 v94, v94, v106
	v_add_f32_e32 v91, 0, v3
	v_mul_f32_e32 v94, 0x3fb8aa3b, v94
	v_add_f32_e32 v2, v135, v91
	v_sub_f32_e32 v91, v92, v106
	v_mul_f32_e32 v91, 0x3fb8aa3b, v91
	v_sub_f32_e32 v92, v93, v106
	v_exp_f32_e32 v91, v91
	v_mul_f32_e32 v92, 0x3fb8aa3b, v92
	v_sub_f32_e32 v93, v95, v106
	v_exp_f32_e32 v92, v92
	v_mul_f32_e32 v93, 0x3fb8aa3b, v93
	v_exp_f32_e32 v93, v93
	v_sub_f32_e32 v95, v124, v106
	v_exp_f32_e32 v94, v94
	v_mul_f32_e32 v95, 0x3fb8aa3b, v95
	v_sub_f32_e32 v124, v125, v106
	v_add_f32_e32 v2, v91, v2
	v_exp_f32_e32 v95, v95
	v_mul_f32_e32 v124, 0x3fb8aa3b, v124
	v_sub_f32_e32 v125, v126, v106
	v_add_f32_e32 v2, v92, v2
	v_exp_f32_e32 v124, v124
	v_mul_f32_e32 v125, 0x3fb8aa3b, v125
	v_sub_f32_e32 v120, v120, v106
	v_add_f32_e32 v2, v93, v2
	v_exp_f32_e32 v125, v125
	v_mul_f32_e32 v120, 0x3fb8aa3b, v120
	v_sub_f32_e32 v121, v121, v106
	v_add_f32_e32 v2, v94, v2
	v_exp_f32_e32 v120, v120
	v_mul_f32_e32 v121, 0x3fb8aa3b, v121
	v_sub_f32_e32 v122, v122, v106
	v_add_f32_e32 v2, v95, v2
	v_exp_f32_e32 v121, v121
	v_mul_f32_e32 v122, 0x3fb8aa3b, v122
	v_sub_f32_e32 v123, v123, v106
	v_add_f32_e32 v2, v124, v2
	v_exp_f32_e32 v122, v122
	v_mul_f32_e32 v123, 0x3fb8aa3b, v123
	v_sub_f32_e32 v116, v116, v106
	v_add_f32_e32 v2, v125, v2
	v_exp_f32_e32 v123, v123
	v_mul_f32_e32 v116, 0x3fb8aa3b, v116
	v_sub_f32_e32 v117, v117, v106
	v_sub_f32_e32 v112, v112, v106
	v_add_f32_e32 v2, v120, v2
	v_exp_f32_e32 v116, v116
	v_mul_f32_e32 v117, 0x3fb8aa3b, v117
	v_sub_f32_e32 v118, v118, v106
	v_mul_f32_e32 v112, 0x3fb8aa3b, v112
	v_add_f32_e32 v2, v121, v2
	v_exp_f32_e32 v117, v117
	v_mul_f32_e32 v118, 0x3fb8aa3b, v118
	v_sub_f32_e32 v119, v119, v106
	v_exp_f32_e32 v126, v112
	v_sub_f32_e32 v112, v113, v106
	v_add_f32_e32 v2, v122, v2
	v_exp_f32_e32 v118, v118
	v_mul_f32_e32 v119, 0x3fb8aa3b, v119
	v_mul_f32_e32 v112, 0x3fb8aa3b, v112
	v_add_f32_e32 v2, v123, v2
	v_exp_f32_e32 v119, v119
	v_exp_f32_e32 v152, v112
	v_sub_f32_e32 v112, v114, v106
	v_sub_f32_e32 v108, v108, v106
	v_add_f32_e32 v2, v116, v2
	v_mul_f32_e32 v112, 0x3fb8aa3b, v112
	v_mul_f32_e32 v108, 0x3fb8aa3b, v108
	v_add_f32_e32 v2, v117, v2
	v_exp_f32_e32 v153, v112
	v_sub_f32_e32 v112, v115, v106
	v_exp_f32_e32 v155, v108
	v_sub_f32_e32 v108, v109, v106
	v_add_f32_e32 v2, v118, v2
	v_mul_f32_e32 v112, 0x3fb8aa3b, v112
	v_mul_f32_e32 v108, 0x3fb8aa3b, v108
	v_add_f32_e32 v2, v119, v2
	v_exp_f32_e32 v154, v112
	v_exp_f32_e32 v160, v108
	v_sub_f32_e32 v108, v110, v106
	v_add_f32_e32 v2, v126, v2
	v_mul_f32_e32 v108, 0x3fb8aa3b, v108
	v_add_f32_e32 v2, v152, v2
	v_exp_f32_e32 v161, v108
	v_sub_f32_e32 v108, v111, v106
	v_add_f32_e32 v2, v153, v2
	v_mul_f32_e32 v108, 0x3fb8aa3b, v108
	v_sub_f32_e32 v104, v104, v106
	v_add_f32_e32 v2, v154, v2
	v_exp_f32_e32 v162, v108
	v_mul_f32_e32 v104, 0x3fb8aa3b, v104
	v_sub_f32_e32 v105, v105, v106
	v_sub_f32_e32 v100, v100, v106
	v_add_f32_e32 v2, v155, v2
	v_exp_f32_e32 v104, v104
	v_mul_f32_e32 v105, 0x3fb8aa3b, v105
	v_sub_f32_e32 v107, v107, v106
	v_mul_f32_e32 v100, 0x3fb8aa3b, v100
	v_add_f32_e32 v2, v160, v2
	v_exp_f32_e32 v105, v105
	v_mul_f32_e32 v107, 0x3fb8aa3b, v107
	v_sub_f32_e32 v108, v127, v106
	v_exp_f32_e32 v163, v100
	v_sub_f32_e32 v100, v101, v106
	v_add_f32_e32 v2, v161, v2
	v_exp_f32_e32 v107, v107
	v_mul_f32_e32 v108, 0x3fb8aa3b, v108
	v_mul_f32_e32 v100, 0x3fb8aa3b, v100
	v_sub_f32_e32 v96, v96, v106
	v_add_f32_e32 v2, v162, v2
	v_exp_f32_e32 v127, v108
	v_exp_f32_e32 v165, v100
	v_sub_f32_e32 v100, v102, v106
	v_mul_f32_e32 v96, 0x3fb8aa3b, v96
	v_add_f32_e32 v2, v104, v2
	v_mul_f32_e32 v100, 0x3fb8aa3b, v100
	v_exp_f32_e32 v168, v96
	v_sub_f32_e32 v96, v97, v106
	v_add_f32_e32 v2, v105, v2
	v_exp_f32_e32 v166, v100
	v_sub_f32_e32 v100, v103, v106
	v_mul_f32_e32 v96, 0x3fb8aa3b, v96
	v_add_f32_e32 v2, v107, v2
	v_mul_f32_e32 v100, 0x3fb8aa3b, v100
	v_exp_f32_e32 v169, v96
	v_sub_f32_e32 v96, v99, v106
	v_add_f32_e32 v2, v127, v2
	v_exp_f32_e32 v167, v100
	v_mul_f32_e32 v96, 0x3fb8aa3b, v96
	v_add_f32_e32 v2, v163, v2
	v_exp_f32_e32 v170, v96
	v_sub_f32_e32 v96, v129, v106
	v_add_f32_e32 v2, v165, v2
	v_mul_f32_e32 v96, 0x3fb8aa3b, v96
	v_add_f32_e32 v2, v166, v2
	v_exp_f32_e32 v129, v96
	v_sub_f32_e32 v96, v98, v106
	v_add_f32_e32 v2, v167, v2
	v_mul_f32_e32 v96, 0x3fb8aa3b, v96
	v_sub_f32_e32 v90, v90, v106
	v_add_f32_e32 v2, v168, v2
	v_exp_f32_e32 v171, v96
	v_mul_f32_e32 v90, 0x3fb8aa3b, v90
	v_sub_f32_e32 v89, v89, v106
	v_add_f32_e32 v2, v169, v2
	v_exp_f32_e32 v172, v90
	v_mul_f32_e32 v89, 0x3fb8aa3b, v89
	v_add_f32_e32 v2, v170, v2
	v_exp_f32_e32 v173, v89
	v_add_f32_e32 v2, v129, v2
	v_add_f32_e32 v2, v171, v2
	v_add_f32_e32 v2, v172, v2
	v_add_f32_e32 v2, v173, v2
	ds_bpermute_b32 v88, v88, v2
	v_cvt_pk_bf16_f32 v89, v91, v92
	v_cvt_pk_bf16_f32 v90, v93, v94
	v_cvt_pk_bf16_f32 v91, v95, v124
	ds_read2_b64 v[92:95], v151 offset1:4
	s_waitcnt lgkmcnt(1)
	v_add_f32_e32 v174, v2, v88
	v_add_u32_e32 v2, s71, v0
	v_cvt_pk_bf16_f32 v88, v3, v135
	v_add_u32_e32 v0, 0x2000, v151
	v_add_u32_e32 v3, 0x4000, v151
	v_add_u32_e32 v124, 0x6000, v151
	ds_read2_b64 v[96:99], v0 offset0:68 offset1:72
	ds_read2_b64 v[100:103], v3 offset0:136 offset1:140
	ds_read2_b64 v[108:111], v124 offset0:204 offset1:208
	ds_read2_b64 v[112:115], v151 offset0:8 offset1:12
	s_waitcnt lgkmcnt(4)
	v_mfma_f32_16x16x32_bf16 v[92:95], v[92:95], v[88:91], 0
	ds_bpermute_b32 v131, v131, v174
	s_ashr_i32 s71, s70, 31
	v_mov_b32_e32 v135, v1
	s_waitcnt lgkmcnt(4)
	v_mfma_f32_16x16x32_bf16 v[96:99], v[96:99], v[88:91], 0
	s_waitcnt lgkmcnt(3)
	v_mfma_f32_16x16x32_bf16 v[100:103], v[100:103], v[88:91], 0
	s_waitcnt lgkmcnt(2)
	v_mfma_f32_16x16x32_bf16 v[88:91], v[108:111], v[88:91], 0
	v_cvt_pk_bf16_f32 v108, v125, v120
	v_cvt_pk_bf16_f32 v109, v121, v122
	v_cvt_pk_bf16_f32 v110, v123, v116
	v_cvt_pk_bf16_f32 v111, v117, v118
	s_waitcnt lgkmcnt(1)
	s_nop 0
	v_mfma_f32_16x16x32_bf16 v[92:95], v[112:115], v[108:111], v[92:95]
	ds_read2_b64 v[112:115], v0 offset0:76 offset1:80
	s_waitcnt lgkmcnt(0)
	v_mfma_f32_16x16x32_bf16 v[96:99], v[112:115], v[108:111], v[96:99]
	ds_read2_b64 v[112:115], v3 offset0:144 offset1:148
	s_waitcnt lgkmcnt(0)
	v_mfma_f32_16x16x32_bf16 v[100:103], v[112:115], v[108:111], v[100:103]
	ds_read2_b64 v[112:115], v124 offset0:212 offset1:216
	s_waitcnt lgkmcnt(0)
	v_mfma_f32_16x16x32_bf16 v[88:91], v[112:115], v[108:111], v[88:91]
	ds_read2_b64 v[112:115], v151 offset0:16 offset1:20
	v_cvt_pk_bf16_f32 v108, v119, v126
	v_cvt_pk_bf16_f32 v109, v152, v153
	v_cvt_pk_bf16_f32 v110, v154, v155
	v_cvt_pk_bf16_f32 v111, v160, v161
	s_waitcnt lgkmcnt(0)
	s_nop 0
	v_mfma_f32_16x16x32_bf16 v[92:95], v[112:115], v[108:111], v[92:95]
	ds_read2_b64 v[112:115], v0 offset0:84 offset1:88
	s_waitcnt lgkmcnt(0)
	v_mfma_f32_16x16x32_bf16 v[96:99], v[112:115], v[108:111], v[96:99]
	ds_read2_b64 v[112:115], v3 offset0:152 offset1:156
	s_waitcnt lgkmcnt(0)
	v_mfma_f32_16x16x32_bf16 v[100:103], v[112:115], v[108:111], v[100:103]
	ds_read2_b64 v[112:115], v124 offset0:220 offset1:224
	s_waitcnt lgkmcnt(0)
	v_mfma_f32_16x16x32_bf16 v[88:91], v[112:115], v[108:111], v[88:91]
	ds_read2_b64 v[112:115], v151 offset0:24 offset1:28
	v_cvt_pk_bf16_f32 v108, v162, v104
	v_cvt_pk_bf16_f32 v109, v105, v107
	v_cvt_pk_bf16_f32 v110, v127, v163
	v_cvt_pk_bf16_f32 v111, v165, v166
	v_add_f32_e32 v107, v174, v131
	s_waitcnt lgkmcnt(0)
	v_mfma_f32_16x16x32_bf16 v[92:95], v[112:115], v[108:111], v[92:95]
	ds_read2_b64 v[112:115], v0 offset0:92 offset1:96
	s_waitcnt lgkmcnt(0)
	v_mfma_f32_16x16x32_bf16 v[96:99], v[112:115], v[108:111], v[96:99]
	ds_read2_b64 v[112:115], v3 offset0:160 offset1:164
	s_waitcnt lgkmcnt(0)
	v_mfma_f32_16x16x32_bf16 v[112:115], v[112:115], v[108:111], v[100:103]
	s_nop 2
	ds_read2_b64 v[100:103], v124 offset0:228 offset1:232
	s_waitcnt lgkmcnt(0)
	v_mfma_f32_16x16x32_bf16 v[88:91], v[100:103], v[108:111], v[88:91]
	ds_read2_b64 v[100:103], v151 offset0:32 offset1:36
	v_cvt_pk_bf16_f32 v108, v167, v168
	v_cvt_pk_bf16_f32 v109, v169, v170
	v_cvt_pk_bf16_f32 v110, v129, v171
	v_cvt_pk_bf16_f32 v111, v172, v173
	s_waitcnt lgkmcnt(0)
	s_nop 0
	v_mfma_f32_16x16x32_bf16 v[100:103], v[100:103], v[108:111], v[92:95]
	s_nop 2
	ds_read2_b64 v[92:95], v0 offset0:100 offset1:104
	v_div_scale_f32 v0, s[64:65], v107, v107, 1.0
	s_waitcnt lgkmcnt(0)
	v_mfma_f32_16x16x32_bf16 v[96:99], v[92:95], v[108:111], v[96:99]
	ds_read2_b64 v[92:95], v3 offset0:168 offset1:172
	v_rcp_f32_e32 v3, v0
	s_lshl_b64 s[64:65], s[70:71], 25
	s_waitcnt lgkmcnt(0)
	v_mfma_f32_16x16x32_bf16 v[92:95], v[92:95], v[108:111], v[112:115]
	s_nop 2
	ds_read2_b64 v[112:115], v124 offset0:236 offset1:240
	v_fma_f32 v104, -v0, v3, 1.0
	v_fmac_f32_e32 v3, v104, v3
	v_div_scale_f32 v104, vcc, 1.0, v107, 1.0
	v_mul_f32_e32 v105, v104, v3
	s_waitcnt lgkmcnt(0)
	v_mfma_f32_16x16x32_bf16 v[88:91], v[112:115], v[108:111], v[88:91]
	v_fma_f32 v108, -v0, v105, v104
	v_fmac_f32_e32 v105, v108, v3
	v_fma_f32 v0, -v0, v105, v104
	v_div_fmas_f32 v0, v0, v3, v105
	s_add_u32 s64, s52, s64
	v_ashrrev_i32_e32 v3, 31, v2
	s_addc_u32 s65, s53, s65
	v_lshlrev_b64 v[104:105], 11, v[2:3]
	v_div_fixup_f32 v0, v0, v107, 1.0
	v_lshl_add_u64 v[104:105], s[64:65], 0, v[104:105]
	s_lshl_b32 s72, s79, 7
	v_lshl_add_u64 v[104:105], v[104:105], 0, s[72:73]
	v_pk_mul_f32 v[100:101], v[0:1], v[100:101] op_sel_hi:[0,1]
	v_pk_mul_f32 v[102:103], v[0:1], v[102:103] op_sel_hi:[0,1]
	v_pk_mul_f32 v[96:97], v[0:1], v[96:97] op_sel_hi:[0,1]
	v_pk_mul_f32 v[98:99], v[0:1], v[98:99] op_sel_hi:[0,1]
	v_pk_mul_f32 v[92:93], v[0:1], v[92:93] op_sel_hi:[0,1]
	v_pk_mul_f32 v[94:95], v[0:1], v[94:95] op_sel_hi:[0,1]
	v_pk_mul_f32 v[88:89], v[0:1], v[88:89] op_sel_hi:[0,1]
	v_pk_mul_f32 v[90:91], v[0:1], v[90:91] op_sel_hi:[0,1]
	v_lshl_add_u64 v[104:105], v[104:105], 0, v[134:135]
	v_cvt_pk_bf16_f32 v100, v100, v101
	v_cvt_pk_bf16_f32 v101, v102, v103
	v_cvt_pk_bf16_f32 v96, v96, v97
	v_cvt_pk_bf16_f32 v97, v98, v99
	v_cvt_pk_bf16_f32 v92, v92, v93
	v_cvt_pk_bf16_f32 v93, v94, v95
	v_cvt_pk_bf16_f32 v88, v88, v89
	v_cvt_pk_bf16_f32 v89, v90, v91
	global_store_dwordx2 v[104:105], v[100:101], off
	global_store_dwordx2 v[104:105], v[96:97], off offset:32
	global_store_dwordx2 v[104:105], v[92:93], off offset:64
	global_store_dwordx2 v[104:105], v[88:89], off offset:96
	s_mov_b64 s[64:65], exec
	v_readlane_b32 s68, v255, 11
	v_readlane_b32 s69, v255, 12
	s_and_b64 s[68:69], s[64:65], s[68:69]
	s_mov_b64 exec, s[68:69]
	s_cbranch_execz .LBB0_749
	s_mov_b32 s68, 0x800000
	v_cmp_gt_f32_e32 vcc, s68, v107
	s_mov_b32 s68, 0x3f317217
	v_lshlrev_b64 v[2:3], 6, v[2:3]
	v_cndmask_b32_e64 v0, 0, 32, vcc
	v_ldexp_f32 v0, v107, v0
	v_log_f32_e32 v0, v0
	v_cndmask_b32_e32 v88, 0, v212, vcc
	v_mul_f32_e32 v89, 0x3f317217, v0
	v_fma_f32 v89, v0, s68, -v89
	s_mov_b32 s68, 0x7f800000
	v_fmac_f32_e32 v89, 0x3377d1cf, v0
	v_cmp_lt_f32_e64 vcc, |v0|, s68
	s_lshl_b64 s[68:69], s[70:71], 20
	v_fmac_f32_e32 v89, 0x3f317217, v0
	s_add_u32 s68, s55, s68
	v_readlane_b32 s70, v254, 44
	v_cndmask_b32_e32 v0, v0, v89, vcc
	s_addc_u32 s69, s70, s69
	v_sub_f32_e32 v0, v0, v88
	v_lshl_add_u64 v[2:3], s[68:69], 0, v[2:3]
	s_lshl_b32 s72, s79, 2
	v_add_f32_e32 v0, v106, v0
	v_lshl_add_u64 v[2:3], v[2:3], 0, s[72:73]
	global_store_dword v[2:3], v0, off
	s_branch .LBB0_749
